# k31 + the 8th gates-epilogue copy vectorized as well (all bj=0 copies)
# speedup vs baseline: 1.0214x; 1.0019x over previous
.LBB0_836:
	s_andn2_b64 vcc, exec, s[4:5]
	s_cbranch_vccnz .LBB0_858
	s_and_saveexec_b64 s[0:1], s[10:11]
	s_xor_b64 s[0:1], exec, s[0:1]
	s_cbranch_execz .LBB0_855
.LBB0_855:
	s_andn2_saveexec_b64 s[0:1], s[0:1]
	s_cbranch_execz .LBB0_857
	s_waitcnt lgkmcnt(0)
	v_mul_f32_e32 v0, 0xbfb8aa3b, v66
	v_exp_f32_e32 v66, v0
	v_mul_f32_e32 v0, 0xbfb8aa3b, v70
	v_exp_f32_e32 v70, v0
	v_mul_f32_e32 v0, 0xbfb8aa3b, v67
	v_exp_f32_e32 v67, v0
	v_mul_f32_e32 v0, 0xbfb8aa3b, v71
	v_exp_f32_e32 v71, v0
	v_mul_f32_e32 v0, 0xbfb8aa3b, v68
	v_exp_f32_e32 v68, v0
	v_mul_f32_e32 v0, 0xbfb8aa3b, v72
	v_exp_f32_e32 v72, v0
	v_mul_f32_e32 v0, 0xbfb8aa3b, v69
	v_exp_f32_e32 v69, v0
	v_pk_add_f32 v[66:67], v[66:67], 1.0 op_sel_hi:[1,0]
	v_pk_add_f32 v[70:71], v[70:71], 1.0 op_sel_hi:[1,0]
	v_pk_add_f32 v[68:69], v[68:69], 1.0 op_sel_hi:[1,0]
	s_nop 0
	v_div_scale_f32 v0, s[4:5], v69, v69, 1.0
	v_rcp_f32_e32 v74, v0
	s_nop 0
	v_fma_f32 v75, -v0, v74, 1.0
	v_fmac_f32_e32 v74, v75, v74
	v_div_scale_f32 v75, vcc, 1.0, v69, 1.0
	v_mul_f32_e32 v76, v75, v74
	v_fma_f32 v77, -v0, v76, v75
	v_fmac_f32_e32 v76, v77, v74
	v_fma_f32 v0, -v0, v76, v75
	v_div_fmas_f32 v0, v0, v74, v76
	v_div_fixup_f32 v69, v0, v69, 1.0
	v_div_scale_f32 v0, s[4:5], v68, v68, 1.0
	v_rcp_f32_e32 v74, v0
	s_nop 0
	v_fma_f32 v75, -v0, v74, 1.0
	v_fmac_f32_e32 v74, v75, v74
	v_div_scale_f32 v75, vcc, 1.0, v68, 1.0
	v_mul_f32_e32 v76, v75, v74
	v_fma_f32 v77, -v0, v76, v75
	v_fmac_f32_e32 v76, v77, v74
	v_fma_f32 v0, -v0, v76, v75
	v_div_fmas_f32 v0, v0, v74, v76
	v_div_fixup_f32 v68, v0, v68, 1.0
	v_div_scale_f32 v0, s[4:5], v67, v67, 1.0
	v_rcp_f32_e32 v74, v0
	s_nop 0
	v_fma_f32 v75, -v0, v74, 1.0
	v_fmac_f32_e32 v74, v75, v74
	v_div_scale_f32 v75, vcc, 1.0, v67, 1.0
	v_mul_f32_e32 v76, v75, v74
	v_fma_f32 v77, -v0, v76, v75
	v_fmac_f32_e32 v76, v77, v74
	v_fma_f32 v0, -v0, v76, v75
	v_div_fmas_f32 v0, v0, v74, v76
	v_div_fixup_f32 v67, v0, v67, 1.0
	v_div_scale_f32 v0, s[4:5], v66, v66, 1.0
	v_rcp_f32_e32 v74, v0
	s_nop 0
	v_fma_f32 v75, -v0, v74, 1.0
	v_fmac_f32_e32 v74, v75, v74
	v_div_scale_f32 v75, vcc, 1.0, v66, 1.0
	v_mul_f32_e32 v76, v75, v74
	v_fma_f32 v77, -v0, v76, v75
	v_fmac_f32_e32 v76, v77, v74
	v_fma_f32 v0, -v0, v76, v75
	v_div_fmas_f32 v0, v0, v74, v76
	v_div_fixup_f32 v66, v0, v66, 1.0
	v_mul_f32_e32 v0, 0xbfb8aa3b, v73
	v_exp_f32_e32 v73, v0
	s_nop 0
	v_pk_add_f32 v[72:73], v[72:73], 1.0 op_sel_hi:[1,0]
	s_nop 0
	v_div_scale_f32 v0, s[4:5], v73, v73, 1.0
	v_rcp_f32_e32 v74, v0
	s_nop 0
	v_fma_f32 v75, -v0, v74, 1.0
	v_fmac_f32_e32 v74, v75, v74
	v_div_scale_f32 v75, vcc, 1.0, v73, 1.0
	v_mul_f32_e32 v76, v75, v74
	v_fma_f32 v77, -v0, v76, v75
	v_fmac_f32_e32 v76, v77, v74
	v_fma_f32 v0, -v0, v76, v75
	v_div_fmas_f32 v0, v0, v74, v76
	v_div_fixup_f32 v73, v0, v73, 1.0
	v_div_scale_f32 v0, s[4:5], v72, v72, 1.0
	v_rcp_f32_e32 v74, v0
	s_nop 0
	v_fma_f32 v75, -v0, v74, 1.0
	v_fmac_f32_e32 v74, v75, v74
	v_div_scale_f32 v75, vcc, 1.0, v72, 1.0
	v_mul_f32_e32 v76, v75, v74
	v_fma_f32 v77, -v0, v76, v75
	v_fmac_f32_e32 v76, v77, v74
	v_fma_f32 v0, -v0, v76, v75
	v_div_fmas_f32 v0, v0, v74, v76
	v_div_fixup_f32 v72, v0, v72, 1.0
	v_div_scale_f32 v0, s[4:5], v71, v71, 1.0
	v_rcp_f32_e32 v74, v0
	s_nop 0
	v_fma_f32 v75, -v0, v74, 1.0
	v_fmac_f32_e32 v74, v75, v74
	v_div_scale_f32 v75, vcc, 1.0, v71, 1.0
	v_mul_f32_e32 v76, v75, v74
	v_fma_f32 v77, -v0, v76, v75
	v_fmac_f32_e32 v76, v77, v74
	v_fma_f32 v0, -v0, v76, v75
	v_div_fmas_f32 v0, v0, v74, v76
	v_div_fixup_f32 v71, v0, v71, 1.0
	v_div_scale_f32 v0, s[4:5], v70, v70, 1.0
	v_rcp_f32_e32 v74, v0
	s_movk_i32 s4, 0x60
	v_fma_f32 v75, -v0, v74, 1.0
	v_fmac_f32_e32 v74, v75, v74
	v_div_scale_f32 v75, vcc, 1.0, v70, 1.0
	v_mul_f32_e32 v76, v75, v74
	v_fma_f32 v77, -v0, v76, v75
	v_fmac_f32_e32 v76, v77, v74
	v_fma_f32 v0, -v0, v76, v75
	v_div_fmas_f32 v0, v0, v74, v76
	v_mov_b64_e32 v[74:75], s[20:21]
	v_mad_i64_i32 v[74:75], s[4:5], v84, s4, v[74:75]
	v_lshl_add_u64 v[74:75], v[218:219], 2, v[74:75]
	v_div_fixup_f32 v70, v0, v70, 1.0
	global_store_dwordx4 v[74:75], v[66:69], off
	global_store_dwordx4 v[74:75], v[70:73], off offset:16
.LBB0_857:
	s_or_b64 exec, exec, s[0:1]
	v_and_b32_e32 v74, 15, v240
	v_or_b32_e32 v74, 48, v74
	v_lshlrev_b32_e32 v74, 2, v74
	ds_bpermute_b32 v70, v74, v66
	ds_bpermute_b32 v71, v74, v67
	ds_bpermute_b32 v72, v74, v68
	ds_bpermute_b32 v73, v74, v69
	v_readlane_b32 s4, v254, 26
	v_readlane_b32 s5, v254, 27
	s_nop 4
	s_load_dword s31, s[4:5], 0xc
	s_waitcnt lgkmcnt(0)
	v_add_f32_e32 v0, s31, v73
	s_load_dword s31, s[4:5], 0x0
	s_waitcnt lgkmcnt(0)
	v_add_f32_e32 v75, s31, v70
	v_cmp_eq_u32_e32 vcc, 0, v246
	s_nop 1
	v_cndmask_b32_e32 v0, v0, v75, vcc
	s_load_dword s31, s[4:5], 0x4
	s_waitcnt lgkmcnt(0)
	v_add_f32_e32 v75, s31, v71
	v_cmp_eq_u32_e32 vcc, 1, v246
	s_nop 1
	v_cndmask_b32_e32 v0, v0, v75, vcc
	s_load_dword s31, s[4:5], 0x8
	s_waitcnt lgkmcnt(0)
	v_add_f32_e32 v75, s31, v72
	v_cmp_eq_u32_e32 vcc, 2, v246
	s_nop 1
	v_cndmask_b32_e32 v0, v0, v75, vcc
	v_cmp_nlt_f32_e32 vcc, 0, v0
	s_and_saveexec_b64 s[4:5], vcc
	s_xor_b64 s[4:5], exec, s[4:5]
	s_cbranch_execz .LBB0_840
	v_mul_f32_e32 v66, 0x3fb8aa3b, v0
	v_exp_f32_e32 v66, v66
	s_mov_b32 s8, 0x3f2aaaab
	v_add_f32_e32 v72, 1.0, v66
	v_frexp_mant_f32_e32 v74, v72
	v_cvt_f64_f32_e32 v[70:71], v72
	v_frexp_exp_i32_f64_e32 v70, v[70:71]
	v_cmp_gt_f32_e32 vcc, s8, v74
	v_add_f32_e32 v73, -1.0, v72
	v_sub_f32_e32 v75, v73, v72
	v_subbrev_co_u32_e32 v78, vcc, 0, v70, vcc
	v_sub_u32_e32 v70, 0, v78
	v_sub_f32_e32 v73, v66, v73
	v_add_f32_e32 v75, 1.0, v75
	v_ldexp_f32 v71, v72, v70
	v_add_f32_e32 v73, v73, v75
	v_add_f32_e32 v72, -1.0, v71
	v_add_f32_e32 v74, 1.0, v71
	v_ldexp_f32 v70, v73, v70
	v_add_f32_e32 v73, 1.0, v72
	v_add_f32_e32 v75, -1.0, v74
	v_sub_f32_e32 v73, v71, v73
	v_sub_f32_e32 v71, v71, v75
	v_add_f32_e32 v73, v70, v73
	v_add_f32_e32 v70, v70, v71
	v_add_f32_e32 v79, v74, v70
	v_rcp_f32_e32 v81, v79
	v_sub_f32_e32 v71, v79, v74
	v_sub_f32_e32 v80, v70, v71
	v_add_f32_e32 v71, v72, v73
	v_mul_f32_e32 v83, v71, v81
	v_sub_f32_e32 v70, v71, v72
	v_mul_f32_e32 v72, v79, v83
	v_fma_f32 v74, v83, v79, -v72
	v_fmac_f32_e32 v74, v83, v80
	v_sub_f32_e32 v82, v73, v70
	v_add_f32_e32 v70, v72, v74
	v_sub_f32_e32 v73, v71, v70
	v_pk_add_f32 v[76:77], v[70:71], v[72:73] neg_lo:[0,1] neg_hi:[0,1]
	v_mov_b32_e32 v75, v70
	v_pk_add_f32 v[70:71], v[76:77], v[74:75] neg_lo:[0,1] neg_hi:[0,1]
	s_mov_b32 s8, 0x3f317218
	v_add_f32_e32 v71, v82, v71
	v_add_f32_e32 v70, v70, v71
	v_add_f32_e32 v71, v73, v70
	v_mul_f32_e32 v82, v81, v71
	v_mul_f32_e32 v72, v79, v82
	v_fma_f32 v74, v82, v79, -v72
	v_fmac_f32_e32 v74, v82, v80
	v_sub_f32_e32 v73, v73, v71
	v_add_f32_e32 v79, v70, v73
	v_add_f32_e32 v70, v72, v74
	v_sub_f32_e32 v73, v71, v70
	v_pk_add_f32 v[76:77], v[70:71], v[72:73] neg_lo:[0,1] neg_hi:[0,1]
	v_mov_b32_e32 v75, v70
	v_pk_add_f32 v[70:71], v[76:77], v[74:75] neg_lo:[0,1] neg_hi:[0,1]
	s_nop 0
	v_add_f32_e32 v71, v79, v71
	v_add_f32_e32 v70, v70, v71
	v_add_f32_e32 v71, v83, v82
	v_add_f32_e32 v70, v73, v70
	v_sub_f32_e32 v72, v71, v83
	v_mul_f32_e32 v70, v81, v70
	v_sub_f32_e32 v72, v82, v72
	v_add_f32_e32 v72, v72, v70
	v_add_f32_e32 v74, v71, v72
	v_mul_f32_e32 v75, v74, v74
	v_fmamk_f32 v70, v75, 0x3e9b6dac, v236
	v_fmaak_f32 v205, v75, v70, 0x3f2aaada
	v_cvt_f32_i32_e32 v70, v78
	v_sub_f32_e32 v71, v74, v71
	v_sub_f32_e32 v71, v72, v71
	v_ldexp_f32 v76, v71, 1
	v_mul_f32_e32 v71, v74, v75
	v_ldexp_f32 v73, v74, 1
	v_pk_mul_f32 v[74:75], v[70:71], v[204:205]
	s_nop 0
	v_fma_f32 v72, v70, s8, -v74
	v_fmac_f32_e32 v72, 0xb102e308, v70
	v_pk_add_f32 v[70:71], v[74:75], v[72:73]
	s_mov_b32 s8, 0x7f800000
	v_sub_f32_e32 v73, v71, v73
	v_sub_f32_e32 v73, v75, v73
	v_add_f32_e32 v77, v76, v73
	v_mov_b32_e32 v76, v74
	v_pk_add_f32 v[74:75], v[70:71], v[74:75] neg_lo:[0,1] neg_hi:[0,1]
	v_pk_add_f32 v[78:79], v[70:71], v[76:77]
	v_mov_b32_e32 v73, v70
	v_mov_b32_e32 v75, v79
	v_pk_add_f32 v[80:81], v[72:73], v[74:75] neg_lo:[0,1] neg_hi:[0,1]
	v_pk_add_f32 v[72:73], v[72:73], v[74:75]
	v_mov_b32_e32 v76, v77
	v_pk_add_f32 v[74:75], v[72:73], v[70:71] op_sel:[1,0] op_sel_hi:[0,1] neg_lo:[0,1] neg_hi:[0,1]
	v_pk_add_f32 v[82:83], v[78:79], v[74:75] op_sel_hi:[1,0] neg_lo:[0,1] neg_hi:[0,1]
	v_mov_b32_e32 v78, v79
	v_mov_b32_e32 v79, v73
	v_pk_mov_b32 v[74:75], v[70:71], v[74:75] op_sel:[1,0]
	v_mov_b32_e32 v77, v70
	v_pk_add_f32 v[74:75], v[78:79], v[74:75] neg_lo:[0,1] neg_hi:[0,1]
	v_mov_b32_e32 v82, v80
	v_pk_add_f32 v[70:71], v[76:77], v[74:75] neg_lo:[0,1] neg_hi:[0,1]
	v_mov_b32_e32 v81, v73
	v_pk_add_f32 v[74:75], v[82:83], v[70:71]
	v_cmp_neq_f32_e32 vcc, s8, v66
	v_pk_add_f32 v[76:77], v[74:75], v[74:75] op_sel:[0,1] op_sel_hi:[1,0]
	s_mov_b32 s8, 0x33800000
	v_pk_add_f32 v[72:73], v[72:73], v[76:77] op_sel:[1,0] op_sel_hi:[0,1]
	v_mov_b32_e32 v75, v72
	v_pk_add_f32 v[78:79], v[74:75], v[80:81] neg_lo:[0,1] neg_hi:[0,1]
	v_mov_b32_e32 v71, v76
	v_sub_f32_e32 v73, v74, v78
	v_pk_add_f32 v[70:71], v[70:71], v[78:79] neg_lo:[0,1] neg_hi:[0,1]
	v_sub_f32_e32 v73, v80, v73
	v_add_f32_e32 v70, v70, v73
	v_add_f32_e32 v70, v70, v71
	v_add_f32_e32 v70, v72, v70
	v_cndmask_b32_e32 v70, v237, v70, vcc
	v_cmp_ngt_f32_e32 vcc, -1.0, v66
	s_nop 1
	v_cndmask_b32_e32 v70, v238, v70, vcc
	v_cmp_neq_f32_e32 vcc, -1.0, v66
	s_nop 1
	v_cndmask_b32_e32 v70, v239, v70, vcc
	v_cmp_lt_f32_e64 vcc, |v66|, s8
	s_nop 1
	v_cndmask_b32_e32 v66, v70, v66, vcc
	v_sub_f32_e32 v66, v0, v66

.LBB0_842:
	s_or_b64 exec, exec, s[4:5]
	v_lshlrev_b32_e32 v72, 2, v85
	v_lshlrev_b32_e32 v0, 2, v86
	v_add_u32_e32 v72, v72, v246
	v_ashrrev_i32_e32 v73, 31, v72
	v_lshl_add_u64 v[70:71], s[84:85], 0, v[0:1]
	v_lshlrev_b64 v[74:75], 13, v[72:73]
	v_lshl_add_u64 v[74:75], v[70:71], 0, v[74:75]
	v_readlane_b32 s4, v254, 26
	global_store_dword v[74:75], v66, off
